# P0: streaming (nt) loads of the x rows, write-through (sc1) stores of the bf16 x rows and transposed weight tiles
# speedup vs baseline: 1.0407x; 1.0129x over previous
.Lp0z_after:
	s_cmp_eq_u32 s59, 0
	s_cbranch_scc1 .Lp0z_advance
	s_waitcnt lgkmcnt(0)
	s_barrier
	s_add_i32 s16, s62, 0
	s_and_b32 s16, s16, 15
	s_lshl_b32 s16, s16, 2
	s_lshl_b32 s17, s15, 4
	s_add_i32 s17, s17, 0
	s_lshl_b32 s17, s17, 10
	v_xor_b32_e32 v11, s16, v7
	v_lshl_add_u32 v11, v11, 2, v8
	v_add_u32_e32 v11, s17, v11
	v_xor_b32_e32 v12, 16, v11
	ds_read_b128 v[156:159], v11
	ds_read_b128 v[160:163], v12
	s_add_i32 s16, s62, 0
	s_and_b32 s16, s16, 15
	s_lshl_b32 s16, s16, 2
	s_lshl_b32 s17, s15, 4
	s_add_i32 s17, s17, 2
	s_lshl_b32 s17, s17, 10
	v_xor_b32_e32 v11, s16, v7
	v_lshl_add_u32 v11, v11, 2, v8
	v_add_u32_e32 v11, s17, v11
	v_xor_b32_e32 v12, 16, v11
	ds_read_b128 v[164:167], v11
	ds_read_b128 v[168:171], v12
	s_add_i32 s16, s62, 1
	s_and_b32 s16, s16, 15
	s_lshl_b32 s16, s16, 2
	s_lshl_b32 s17, s15, 4
	s_add_i32 s17, s17, 4
	s_lshl_b32 s17, s17, 10
	v_xor_b32_e32 v11, s16, v7
	v_lshl_add_u32 v11, v11, 2, v8
	v_add_u32_e32 v11, s17, v11
	v_xor_b32_e32 v12, 16, v11
	ds_read_b128 v[172:175], v11
	ds_read_b128 v[176:179], v12
	s_add_i32 s16, s62, 1
	s_and_b32 s16, s16, 15
	s_lshl_b32 s16, s16, 2
	s_lshl_b32 s17, s15, 4
	s_add_i32 s17, s17, 6
	s_lshl_b32 s17, s17, 10
	v_xor_b32_e32 v11, s16, v7
	v_lshl_add_u32 v11, v11, 2, v8
	v_add_u32_e32 v11, s17, v11
	v_xor_b32_e32 v12, 16, v11
	ds_read_b128 v[180:183], v11
	ds_read_b128 v[184:187], v12
	s_waitcnt lgkmcnt(6)
	v_pk_mul_f32 v[156:157], v[156:157], v[140:141]
	v_pk_mul_f32 v[158:159], v[158:159], v[142:143]
	v_pk_mul_f32 v[160:161], v[160:161], v[144:145]
	v_pk_mul_f32 v[162:163], v[162:163], v[146:147]
	v_cvt_pk_bf16_f32 v128, v156, v157
	v_cvt_pk_bf16_f32 v129, v158, v159
	v_cvt_pk_bf16_f32 v130, v160, v161
	v_cvt_pk_bf16_f32 v131, v162, v163
	global_store_dwordx4 v10, v[128:131], s[26:27] sc1
	s_add_u32 s26, s26, s63
	s_addc_u32 s27, s27, 0
	s_waitcnt lgkmcnt(4)
	v_pk_mul_f32 v[164:165], v[164:165], v[140:141]
	v_pk_mul_f32 v[166:167], v[166:167], v[142:143]
	v_pk_mul_f32 v[168:169], v[168:169], v[144:145]
	v_pk_mul_f32 v[170:171], v[170:171], v[146:147]
	v_cvt_pk_bf16_f32 v132, v164, v165
	v_cvt_pk_bf16_f32 v133, v166, v167
	v_cvt_pk_bf16_f32 v134, v168, v169
	v_cvt_pk_bf16_f32 v135, v170, v171
	global_store_dwordx4 v10, v[132:135], s[26:27] sc1
	s_add_u32 s26, s26, s63
	s_addc_u32 s27, s27, 0
	s_waitcnt lgkmcnt(2)
	v_pk_mul_f32 v[172:173], v[172:173], v[140:141]
	v_pk_mul_f32 v[174:175], v[174:175], v[142:143]
	v_pk_mul_f32 v[176:177], v[176:177], v[144:145]
	v_pk_mul_f32 v[178:179], v[178:179], v[146:147]
	v_cvt_pk_bf16_f32 v128, v172, v173
	v_cvt_pk_bf16_f32 v129, v174, v175
	v_cvt_pk_bf16_f32 v130, v176, v177
	v_cvt_pk_bf16_f32 v131, v178, v179
	global_store_dwordx4 v10, v[128:131], s[26:27] sc1
	s_add_u32 s26, s26, s63
	s_addc_u32 s27, s27, 0
	s_waitcnt lgkmcnt(0)
	v_pk_mul_f32 v[180:181], v[180:181], v[140:141]
	v_pk_mul_f32 v[182:183], v[182:183], v[142:143]
	v_pk_mul_f32 v[184:185], v[184:185], v[144:145]
	v_pk_mul_f32 v[186:187], v[186:187], v[146:147]
	v_cvt_pk_bf16_f32 v132, v180, v181
	v_cvt_pk_bf16_f32 v133, v182, v183
	v_cvt_pk_bf16_f32 v134, v184, v185
	v_cvt_pk_bf16_f32 v135, v186, v187
	global_store_dwordx4 v10, v[132:135], s[26:27] sc1
	s_add_u32 s26, s26, s63
	s_addc_u32 s27, s27, 0
	s_add_i32 s16, s62, 2
	s_and_b32 s16, s16, 15
	s_lshl_b32 s16, s16, 2
	s_lshl_b32 s17, s15, 4
	s_add_i32 s17, s17, 8
	s_lshl_b32 s17, s17, 10
	v_xor_b32_e32 v11, s16, v7
	v_lshl_add_u32 v11, v11, 2, v8
	v_add_u32_e32 v11, s17, v11
	v_xor_b32_e32 v12, 16, v11
	ds_read_b128 v[156:159], v11
	ds_read_b128 v[160:163], v12
	s_add_i32 s16, s62, 2
	s_and_b32 s16, s16, 15
	s_lshl_b32 s16, s16, 2
	s_lshl_b32 s17, s15, 4
	s_add_i32 s17, s17, 10
	s_lshl_b32 s17, s17, 10
	v_xor_b32_e32 v11, s16, v7
	v_lshl_add_u32 v11, v11, 2, v8
	v_add_u32_e32 v11, s17, v11
	v_xor_b32_e32 v12, 16, v11
	ds_read_b128 v[164:167], v11
	ds_read_b128 v[168:171], v12
	s_add_i32 s16, s62, 3
	s_and_b32 s16, s16, 15
	s_lshl_b32 s16, s16, 2
	s_lshl_b32 s17, s15, 4
	s_add_i32 s17, s17, 12
	s_lshl_b32 s17, s17, 10
	v_xor_b32_e32 v11, s16, v7
	v_lshl_add_u32 v11, v11, 2, v8
	v_add_u32_e32 v11, s17, v11
	v_xor_b32_e32 v12, 16, v11
	ds_read_b128 v[172:175], v11
	ds_read_b128 v[176:179], v12
	s_add_i32 s16, s62, 3
	s_and_b32 s16, s16, 15
	s_lshl_b32 s16, s16, 2
	s_lshl_b32 s17, s15, 4
	s_add_i32 s17, s17, 14
	s_lshl_b32 s17, s17, 10
	v_xor_b32_e32 v11, s16, v7
	v_lshl_add_u32 v11, v11, 2, v8
	v_add_u32_e32 v11, s17, v11
	v_xor_b32_e32 v12, 16, v11
	ds_read_b128 v[180:183], v11
	ds_read_b128 v[184:187], v12
	s_waitcnt lgkmcnt(6)
	v_pk_mul_f32 v[156:157], v[156:157], v[140:141]
	v_pk_mul_f32 v[158:159], v[158:159], v[142:143]
	v_pk_mul_f32 v[160:161], v[160:161], v[144:145]
	v_pk_mul_f32 v[162:163], v[162:163], v[146:147]
	v_cvt_pk_bf16_f32 v128, v156, v157
	v_cvt_pk_bf16_f32 v129, v158, v159
	v_cvt_pk_bf16_f32 v130, v160, v161
	v_cvt_pk_bf16_f32 v131, v162, v163
	global_store_dwordx4 v10, v[128:131], s[26:27] sc1
	s_add_u32 s26, s26, s63
	s_addc_u32 s27, s27, 0
	s_waitcnt lgkmcnt(4)
	v_pk_mul_f32 v[164:165], v[164:165], v[140:141]
	v_pk_mul_f32 v[166:167], v[166:167], v[142:143]
	v_pk_mul_f32 v[168:169], v[168:169], v[144:145]
	v_pk_mul_f32 v[170:171], v[170:171], v[146:147]
	v_cvt_pk_bf16_f32 v132, v164, v165
	v_cvt_pk_bf16_f32 v133, v166, v167
	v_cvt_pk_bf16_f32 v134, v168, v169
	v_cvt_pk_bf16_f32 v135, v170, v171
	global_store_dwordx4 v10, v[132:135], s[26:27] sc1
	s_add_u32 s26, s26, s63
	s_addc_u32 s27, s27, 0
	s_waitcnt lgkmcnt(2)
	v_pk_mul_f32 v[172:173], v[172:173], v[140:141]
	v_pk_mul_f32 v[174:175], v[174:175], v[142:143]
	v_pk_mul_f32 v[176:177], v[176:177], v[144:145]
	v_pk_mul_f32 v[178:179], v[178:179], v[146:147]
	v_cvt_pk_bf16_f32 v128, v172, v173
	v_cvt_pk_bf16_f32 v129, v174, v175
	v_cvt_pk_bf16_f32 v130, v176, v177
	v_cvt_pk_bf16_f32 v131, v178, v179
	global_store_dwordx4 v10, v[128:131], s[26:27] sc1
	s_add_u32 s26, s26, s63
	s_addc_u32 s27, s27, 0
	s_waitcnt lgkmcnt(0)
	v_pk_mul_f32 v[180:181], v[180:181], v[140:141]
	v_pk_mul_f32 v[182:183], v[182:183], v[142:143]
	v_pk_mul_f32 v[184:185], v[184:185], v[144:145]
	v_pk_mul_f32 v[186:187], v[186:187], v[146:147]
	v_cvt_pk_bf16_f32 v132, v180, v181
	v_cvt_pk_bf16_f32 v133, v182, v183
	v_cvt_pk_bf16_f32 v134, v184, v185
	v_cvt_pk_bf16_f32 v135, v186, v187
	global_store_dwordx4 v10, v[132:135], s[26:27] sc1
	s_barrier

.LBB0_79:
	s_or_b64 exec, exec, s[22:23]
	s_add_u32 s6, s6, s14
	s_addc_u32 s7, s7, s15
	s_add_u32 s16, s16, s18
	v_cvt_pk_bf16_f32 v12, v12, v13
	v_cvt_pk_bf16_f32 v13, v14, v15
	v_cvt_pk_bf16_f32 v14, v8, v9
	v_add_co_u32_e32 v8, vcc, 0x3800000, v36
	s_addc_u32 s17, s17, s19
	s_nop 0
	v_addc_co_u32_e32 v9, vcc, 0, v37, vcc
	s_cmpk_gt_i32 s6, 0x43ff
	v_lshl_add_u64 v[32:33], v[32:33], 0, s[20:21]
	v_cvt_pk_bf16_f32 v15, v10, v11
	global_store_dwordx4 v[8:9], v[12:15], off offset:2048 sc1
	v_cvt_pk_bf16_f32 v4, v4, v5
	v_cvt_pk_bf16_f32 v5, v6, v7
	v_cvt_pk_bf16_f32 v6, v0, v1
	v_cvt_pk_bf16_f32 v7, v2, v3
	global_store_dwordx4 v[8:9], v[4:7], off offset:3072 sc1
	s_cbranch_scc1 .LBB0_84
.LBB0_80:
	s_add_i32 s22, s6, 0xffffc000
	s_cmpk_lt_i32 s6, 0x4000
	v_readlane_b32 s36, v252, 0
	s_cselect_b32 s23, s7, 0
	s_cselect_b32 s22, s6, s22
	v_readlane_b32 s37, v252, 1
	v_readlane_b32 s38, v252, 2
	v_readlane_b32 s39, v252, 3
	s_cselect_b32 s25, s37, s39
	s_cselect_b32 s26, s36, s38
	s_lshl_b64 s[22:23], s[22:23], 12
	s_add_u32 s22, s26, s22
	s_addc_u32 s23, s25, s23
	v_lshl_add_u64 v[0:1], s[22:23], 0, v[34:35]
	global_load_dwordx4 v[28:31], v[0:1], off nt
	global_load_dwordx4 v[24:27], v[0:1], off offset:16 nt
	s_waitcnt lgkmcnt(0)
	global_load_dwordx4 v[20:23], v[0:1], off offset:2048 nt
	global_load_dwordx4 v[16:19], v[0:1], off offset:2064 nt
	s_add_u32 s22, s6, 1
	s_addc_u32 s23, s7, 0
	s_add_i32 s25, s6, 0xffffc001
	s_cmpk_lt_i32 s22, 0x4000
	s_cselect_b32 s23, s23, 0
	s_cselect_b32 s22, s22, s25
	s_cselect_b32 s25, s37, s39
	s_cselect_b32 s26, s36, s38
	s_lshl_b64 s[22:23], s[22:23], 12
	s_add_u32 s22, s26, s22
	s_addc_u32 s23, s25, s23
	v_lshl_add_u64 v[4:5], s[22:23], 0, v[34:35]
	global_load_dwordx4 v[8:11], v[4:5], off offset:16 nt
	global_load_dwordx4 v[12:15], v[4:5], off nt
	global_load_dwordx4 v[0:3], v[4:5], off offset:2064 nt
	s_nop 0
	global_load_dwordx4 v[4:7], v[4:5], off offset:2048 nt
	v_readlane_b32 s40, v252, 4
	v_readlane_b32 s41, v252, 5
	v_readlane_b32 s42, v252, 6
	v_readlane_b32 s43, v252, 7
	v_readlane_b32 s44, v252, 8
	v_readlane_b32 s45, v252, 9
	v_readlane_b32 s46, v252, 10
	v_readlane_b32 s47, v252, 11
	v_readlane_b32 s48, v252, 12
	v_readlane_b32 s49, v252, 13
	v_readlane_b32 s50, v252, 14
	v_readlane_b32 s51, v252, 15
	s_waitcnt vmcnt(7)
	v_mul_f32_e32 v36, v29, v29
	v_fmac_f32_e32 v36, v28, v28
	v_fmac_f32_e32 v36, v30, v30
	v_fmac_f32_e32 v36, v31, v31
	s_waitcnt vmcnt(6)
	v_fmac_f32_e32 v36, v24, v24
	v_fmac_f32_e32 v36, v25, v25
	v_fmac_f32_e32 v36, v26, v26
	v_fmac_f32_e32 v36, v27, v27
	s_waitcnt vmcnt(5)
	v_fmac_f32_e32 v36, v20, v20
	v_fmac_f32_e32 v36, v21, v21
	v_fmac_f32_e32 v36, v22, v22
	v_fmac_f32_e32 v36, v23, v23
	s_waitcnt vmcnt(4)
	v_fmac_f32_e32 v36, v16, v16
	v_fmac_f32_e32 v36, v17, v17
	v_fmac_f32_e32 v36, v18, v18
	v_fmac_f32_e32 v36, v19, v19
	ds_bpermute_b32 v37, v39, v36
	s_waitcnt lgkmcnt(0)
	v_add_f32_e32 v36, v36, v37
	ds_bpermute_b32 v37, v40, v36
	s_waitcnt lgkmcnt(0)
	v_add_f32_e32 v36, v36, v37
	ds_bpermute_b32 v37, v41, v36
	s_waitcnt lgkmcnt(0)
	v_add_f32_e32 v36, v36, v37
	ds_bpermute_b32 v37, v42, v36
	s_waitcnt lgkmcnt(0)
	v_add_f32_e32 v36, v36, v37
	ds_bpermute_b32 v37, v43, v36
	s_waitcnt lgkmcnt(0)
	v_add_f32_e32 v36, v36, v37
	ds_bpermute_b32 v37, v44, v36
	s_and_saveexec_b64 s[22:23], s[0:1]
	s_cbranch_execz .LBB0_82
	s_waitcnt lgkmcnt(0)
	v_add_f32_e32 v36, v36, v37
	v_fmamk_f32 v36, v36, 0x3a800000, v45
	v_rsq_f32_e32 v36, v36
	s_add_u32 s26, s10, s16
	s_addc_u32 s27, s11, s17
	global_store_dword v46, v36, s[26:27]
.LBB0_82:
	s_or_b64 exec, exec, s[22:23]
	s_waitcnt vmcnt(2)
	v_mul_f32_e32 v36, v13, v13
	v_fmac_f32_e32 v36, v12, v12
	v_fmac_f32_e32 v36, v14, v14
	v_fmac_f32_e32 v36, v15, v15
	v_fmac_f32_e32 v36, v8, v8
	v_fmac_f32_e32 v36, v9, v9
	v_fmac_f32_e32 v36, v10, v10
	v_fmac_f32_e32 v36, v11, v11
	s_waitcnt vmcnt(0)
	v_fmac_f32_e32 v36, v4, v4
	v_fmac_f32_e32 v36, v5, v5
	v_fmac_f32_e32 v36, v6, v6
	v_fmac_f32_e32 v36, v7, v7
	v_fmac_f32_e32 v36, v0, v0
	v_fmac_f32_e32 v36, v1, v1
	v_fmac_f32_e32 v36, v2, v2
	v_fmac_f32_e32 v36, v3, v3
	s_waitcnt lgkmcnt(0)
	ds_bpermute_b32 v37, v39, v36
	v_cvt_pk_bf16_f32 v28, v28, v29
	v_cvt_pk_bf16_f32 v29, v30, v31
	v_cvt_pk_bf16_f32 v30, v24, v25
	v_cvt_pk_bf16_f32 v31, v26, v27
	s_waitcnt lgkmcnt(0)
	v_add_f32_e32 v36, v36, v37
	ds_bpermute_b32 v37, v40, v36
	s_waitcnt lgkmcnt(0)
	v_add_f32_e32 v47, v36, v37
	ds_bpermute_b32 v48, v41, v47
	v_lshl_add_u64 v[36:37], s[10:11], 0, v[32:33]
	s_waitcnt lgkmcnt(0)
	v_add_f32_e32 v47, v47, v48
	ds_bpermute_b32 v49, v42, v47
	v_add_co_u32_e32 v48, vcc, s24, v36
	s_waitcnt lgkmcnt(0)
	v_add_f32_e32 v25, v47, v49
	ds_bpermute_b32 v26, v43, v25
	v_addc_co_u32_e32 v49, vcc, 0, v37, vcc
	global_store_dwordx4 v[48:49], v[28:31], off sc1
	v_cvt_pk_bf16_f32 v24, v20, v21
	s_waitcnt lgkmcnt(0)
	v_add_f32_e32 v20, v25, v26
	ds_bpermute_b32 v21, v44, v20
	v_cvt_pk_bf16_f32 v25, v22, v23
	v_cvt_pk_bf16_f32 v26, v16, v17
	v_cvt_pk_bf16_f32 v27, v18, v19
	global_store_dwordx4 v[48:49], v[24:27], off offset:1024 sc1
	s_and_saveexec_b64 s[22:23], s[0:1]
	s_cbranch_execz .LBB0_79
	s_waitcnt lgkmcnt(0)
	v_add_f32_e32 v16, v20, v21
	v_fmamk_f32 v16, v16, 0x3a800000, v45
	v_rsq_f32_e32 v16, v16
	s_add_u32 s26, s10, s16
	s_addc_u32 s27, s11, s17
	global_store_dword v46, v16, s[26:27] offset:4
	s_branch .LBB0_79
